# prefetch extended: weight tile K-tiles 0-3 and A K-tiles 2,3
# baseline (speedup 1.0000x reference)
.LBB0_24:
	ds_read_b128 v[154:157], v138
	ds_read_b128 v[158:161], v139
	ds_read_b128 v[162:165], v140
	ds_read_b128 v[194:197], v141
	ds_read_b128 v[198:201], v142
	ds_read_b128 v[202:205], v143
	ds_read_b128 v[206:209], v144
	ds_read_b128 v[210:213], v145
	s_add_u32 s14, s96, s88
	s_addc_u32 s15, s97, s89
	s_add_u32 s14, s14, 0x4000900
	s_addc_u32 s15, s15, 0
	s_add_u32 s36, s42, s88
	s_addc_u32 s37, s43, s89
	s_cmpk_eq_i32 s88, 0x700
	s_cselect_b32 s27, s87, s15
	s_cselect_b32 s26, s86, s14
	s_cselect_b32 s15, s85, s37
	s_cselect_b32 s14, s84, s36
	v_lshl_add_u64 v[166:167], v[130:131], 0, s[88:89]
	s_add_i32 m0, s94, 0xc000
	ds_read_b128 v[214:217], v137
	ds_read_b128 v[218:221], v137 offset:1024
	ds_read_b128 v[222:225], v137 offset:2048
	ds_read_b128 v[226:229], v137 offset:3072
	ds_read_b128 v[230:233], v137 offset:4096
	ds_read_b128 v[234:237], v137 offset:5120
	ds_read_b128 v[238:241], v137 offset:6144
	ds_read_b128 v[242:245], v137 offset:7168
	global_load_lds_dwordx4 v[166:167], off
	v_lshl_add_u64 v[166:167], v[132:133], 0, s[88:89]
	s_mov_b32 m0, s48
	s_nop 0
	global_load_lds_dwordx4 v[166:167], off
	s_waitcnt vmcnt(8)
	s_waitcnt lgkmcnt(0)
	s_barrier
	s_setprio 1
	s_waitcnt lgkmcnt(0)
	v_mfma_f32_16x16x32_bf16 v[124:127], v[154:157], v[214:217], v[124:127]
	v_mfma_f32_16x16x32_bf16 v[120:123], v[162:165], v[214:217], v[120:123]
	v_mfma_f32_16x16x32_bf16 v[116:119], v[154:157], v[222:225], v[116:119]
	v_mfma_f32_16x16x32_bf16 v[112:115], v[162:165], v[222:225], v[112:115]
	v_mfma_f32_16x16x32_bf16 v[108:111], v[154:157], v[230:233], v[108:111]
	v_mfma_f32_16x16x32_bf16 v[104:107], v[162:165], v[230:233], v[104:107]
	v_mfma_f32_16x16x32_bf16 v[76:79], v[154:157], v[238:241], v[76:79]
	v_mfma_f32_16x16x32_bf16 v[72:75], v[162:165], v[238:241], v[72:75]
	v_mfma_f32_16x16x32_bf16 v[124:127], v[158:161], v[218:221], v[124:127]
	v_mfma_f32_16x16x32_bf16 v[120:123], v[194:197], v[218:221], v[120:123]
	v_mfma_f32_16x16x32_bf16 v[116:119], v[158:161], v[226:229], v[116:119]
	v_mfma_f32_16x16x32_bf16 v[112:115], v[194:197], v[226:229], v[112:115]
	v_mfma_f32_16x16x32_bf16 v[108:111], v[158:161], v[234:237], v[108:111]
	v_mfma_f32_16x16x32_bf16 v[104:107], v[194:197], v[234:237], v[104:107]
	v_mfma_f32_16x16x32_bf16 v[76:79], v[158:161], v[242:245], v[76:79]
	v_mfma_f32_16x16x32_bf16 v[72:75], v[194:197], v[242:245], v[72:75]
	s_setprio 0
	s_setprio 1
	v_mfma_f32_16x16x32_bf16 v[100:103], v[198:201], v[214:217], v[100:103]
	v_mfma_f32_16x16x32_bf16 v[96:99], v[206:209], v[214:217], v[96:99]
	v_mfma_f32_16x16x32_bf16 v[92:95], v[198:201], v[222:225], v[92:95]
	v_mfma_f32_16x16x32_bf16 v[88:91], v[206:209], v[222:225], v[88:91]
	v_mfma_f32_16x16x32_bf16 v[84:87], v[198:201], v[230:233], v[84:87]
	v_mfma_f32_16x16x32_bf16 v[80:83], v[206:209], v[230:233], v[80:83]
	v_mfma_f32_16x16x32_bf16 v[52:55], v[198:201], v[238:241], v[52:55]
	v_mfma_f32_16x16x32_bf16 v[44:47], v[206:209], v[238:241], v[44:47]
	v_mfma_f32_16x16x32_bf16 v[100:103], v[202:205], v[218:221], v[100:103]
	v_mfma_f32_16x16x32_bf16 v[96:99], v[210:213], v[218:221], v[96:99]
	v_mfma_f32_16x16x32_bf16 v[92:95], v[202:205], v[226:229], v[92:95]
	v_mfma_f32_16x16x32_bf16 v[88:91], v[210:213], v[226:229], v[88:91]
	v_mfma_f32_16x16x32_bf16 v[84:87], v[202:205], v[234:237], v[84:87]
	v_mfma_f32_16x16x32_bf16 v[80:83], v[210:213], v[234:237], v[80:83]
	v_mfma_f32_16x16x32_bf16 v[52:55], v[202:205], v[242:245], v[52:55]
	v_mfma_f32_16x16x32_bf16 v[44:47], v[210:213], v[242:245], v[44:47]
	s_setprio 0
	s_barrier
	s_mov_b32 m0, s41
	v_lshl_add_u64 v[166:167], s[14:15], 0, v[168:169]
	s_add_u32 s36, s14, 0x40000
	ds_read_b128 v[214:217], v137 offset:16384
	ds_read_b128 v[218:221], v137 offset:17408
	ds_read_b128 v[222:225], v137 offset:18432
	ds_read_b128 v[226:229], v137 offset:19456
	ds_read_b128 v[230:233], v137 offset:20480
	ds_read_b128 v[234:237], v137 offset:21504
	ds_read_b128 v[238:241], v137 offset:22528
	ds_read_b128 v[242:245], v137 offset:23552
	global_load_lds_dwordx4 v[166:167], off
	v_lshl_add_u64 v[246:247], s[14:15], 0, v[128:129]
	s_mov_b32 m0, s59
	s_addc_u32 s37, s15, 0
	global_load_lds_dwordx4 v[246:247], off
	v_lshl_add_u64 v[248:249], s[36:37], 0, v[168:169]
	s_mov_b32 m0, s95
	v_lshl_add_u64 v[250:251], s[26:27], 0, v[128:129]
	global_load_lds_dwordx4 v[248:249], off
	v_lshl_add_u64 v[248:249], s[36:37], 0, v[128:129]
	s_mov_b32 m0, vcc_lo
	s_nop 0
	global_load_lds_dwordx4 v[248:249], off
	v_lshl_add_u64 v[248:249], s[26:27], 0, v[168:169]
	s_mov_b32 m0, s94
	s_nop 0
	global_load_lds_dwordx4 v[248:249], off
	s_mov_b32 m0, vcc_hi
	s_nop 0
	global_load_lds_dwordx4 v[250:251], off
	s_waitcnt vmcnt(8)
	s_waitcnt lgkmcnt(0)
	s_barrier
	s_setprio 1
	s_waitcnt lgkmcnt(0)
	v_mfma_f32_16x16x32_bf16 v[68:71], v[154:157], v[214:217], v[68:71]
	v_mfma_f32_16x16x32_bf16 v[64:67], v[162:165], v[214:217], v[64:67]
	v_mfma_f32_16x16x32_bf16 v[60:63], v[154:157], v[222:225], v[60:63]
	v_mfma_f32_16x16x32_bf16 v[56:59], v[162:165], v[222:225], v[56:59]
	v_mfma_f32_16x16x32_bf16 v[48:51], v[154:157], v[230:233], v[48:51]
	v_mfma_f32_16x16x32_bf16 v[40:43], v[162:165], v[230:233], v[40:43]
	v_mfma_f32_16x16x32_bf16 v[36:39], v[154:157], v[238:241], v[36:39]
	v_mfma_f32_16x16x32_bf16 v[32:35], v[162:165], v[238:241], v[32:35]
	v_mfma_f32_16x16x32_bf16 v[68:71], v[158:161], v[218:221], v[68:71]
	v_mfma_f32_16x16x32_bf16 v[64:67], v[194:197], v[218:221], v[64:67]
	v_mfma_f32_16x16x32_bf16 v[60:63], v[158:161], v[226:229], v[60:63]
	v_mfma_f32_16x16x32_bf16 v[56:59], v[194:197], v[226:229], v[56:59]
	v_mfma_f32_16x16x32_bf16 v[48:51], v[158:161], v[234:237], v[48:51]
	v_mfma_f32_16x16x32_bf16 v[40:43], v[194:197], v[234:237], v[40:43]
	v_mfma_f32_16x16x32_bf16 v[36:39], v[158:161], v[242:245], v[36:39]
	v_mfma_f32_16x16x32_bf16 v[32:35], v[194:197], v[242:245], v[32:35]
	s_setprio 0
	s_setprio 1
	v_mfma_f32_16x16x32_bf16 v[28:31], v[198:201], v[214:217], v[28:31]
	v_mfma_f32_16x16x32_bf16 v[24:27], v[206:209], v[214:217], v[24:27]
	v_mfma_f32_16x16x32_bf16 v[20:23], v[198:201], v[222:225], v[20:23]
	v_mfma_f32_16x16x32_bf16 v[16:19], v[206:209], v[222:225], v[16:19]
	v_mfma_f32_16x16x32_bf16 v[12:15], v[198:201], v[230:233], v[12:15]
	v_mfma_f32_16x16x32_bf16 v[8:11], v[206:209], v[230:233], v[8:11]
	v_mfma_f32_16x16x32_bf16 v[4:7], v[198:201], v[238:241], v[4:7]
	v_mfma_f32_16x16x32_bf16 v[0:3], v[206:209], v[238:241], v[0:3]
	v_mfma_f32_16x16x32_bf16 v[28:31], v[202:205], v[218:221], v[28:31]
	v_mfma_f32_16x16x32_bf16 v[24:27], v[210:213], v[218:221], v[24:27]
	v_mfma_f32_16x16x32_bf16 v[20:23], v[202:205], v[226:229], v[20:23]
	v_mfma_f32_16x16x32_bf16 v[16:19], v[210:213], v[226:229], v[16:19]
	v_mfma_f32_16x16x32_bf16 v[12:15], v[202:205], v[234:237], v[12:15]
	v_mfma_f32_16x16x32_bf16 v[8:11], v[210:213], v[234:237], v[8:11]
	v_mfma_f32_16x16x32_bf16 v[4:7], v[202:205], v[242:245], v[4:7]
	v_mfma_f32_16x16x32_bf16 v[0:3], v[210:213], v[242:245], v[0:3]
	s_setprio 0
	s_barrier
	ds_read_b128 v[154:157], v146
	ds_read_b128 v[158:161], v147
	ds_read_b128 v[162:165], v148
	ds_read_b128 v[194:197], v149
	ds_read_b128 v[198:201], v150
	ds_read_b128 v[202:205], v151
	ds_read_b128 v[206:209], v152
	ds_read_b128 v[210:213], v153
	s_add_u32 s26, s26, 0x40000
	s_addc_u32 s27, s27, 0
	s_mov_b32 m0, s28
	v_lshl_add_u64 v[180:181], s[26:27], 0, v[168:169]
	ds_read_b128 v[214:217], v137 offset:32768
	ds_read_b128 v[218:221], v137 offset:33792
	ds_read_b128 v[222:225], v137 offset:34816
	ds_read_b128 v[226:229], v137 offset:35840
	ds_read_b128 v[230:233], v137 offset:36864
	ds_read_b128 v[234:237], v137 offset:37888
	ds_read_b128 v[238:241], v137 offset:38912
	ds_read_b128 v[242:245], v137 offset:39936
	global_load_lds_dwordx4 v[180:181], off
	v_lshl_add_u64 v[180:181], s[26:27], 0, v[128:129]
	s_mov_b32 m0, s29
	s_nop 0
	global_load_lds_dwordx4 v[180:181], off
	s_waitcnt vmcnt(8)
	s_waitcnt lgkmcnt(0)
	s_barrier
	s_setprio 1
	s_waitcnt lgkmcnt(0)
	v_mfma_f32_16x16x32_bf16 v[124:127], v[154:157], v[214:217], v[124:127]
	v_mfma_f32_16x16x32_bf16 v[120:123], v[162:165], v[214:217], v[120:123]
	v_mfma_f32_16x16x32_bf16 v[116:119], v[154:157], v[222:225], v[116:119]
	v_mfma_f32_16x16x32_bf16 v[112:115], v[162:165], v[222:225], v[112:115]
	v_mfma_f32_16x16x32_bf16 v[108:111], v[154:157], v[230:233], v[108:111]
	v_mfma_f32_16x16x32_bf16 v[104:107], v[162:165], v[230:233], v[104:107]
	v_mfma_f32_16x16x32_bf16 v[76:79], v[154:157], v[238:241], v[76:79]
	v_mfma_f32_16x16x32_bf16 v[72:75], v[162:165], v[238:241], v[72:75]
	v_mfma_f32_16x16x32_bf16 v[124:127], v[158:161], v[218:221], v[124:127]
	v_mfma_f32_16x16x32_bf16 v[120:123], v[194:197], v[218:221], v[120:123]
	v_mfma_f32_16x16x32_bf16 v[116:119], v[158:161], v[226:229], v[116:119]
	v_mfma_f32_16x16x32_bf16 v[112:115], v[194:197], v[226:229], v[112:115]
	v_mfma_f32_16x16x32_bf16 v[108:111], v[158:161], v[234:237], v[108:111]
	v_mfma_f32_16x16x32_bf16 v[104:107], v[194:197], v[234:237], v[104:107]
	v_mfma_f32_16x16x32_bf16 v[76:79], v[158:161], v[242:245], v[76:79]
	v_mfma_f32_16x16x32_bf16 v[72:75], v[194:197], v[242:245], v[72:75]
	s_setprio 0
	s_setprio 1
	v_mfma_f32_16x16x32_bf16 v[100:103], v[198:201], v[214:217], v[100:103]
	v_mfma_f32_16x16x32_bf16 v[96:99], v[206:209], v[214:217], v[96:99]
	v_mfma_f32_16x16x32_bf16 v[92:95], v[198:201], v[222:225], v[92:95]
	v_mfma_f32_16x16x32_bf16 v[88:91], v[206:209], v[222:225], v[88:91]
	v_mfma_f32_16x16x32_bf16 v[84:87], v[198:201], v[230:233], v[84:87]
	v_mfma_f32_16x16x32_bf16 v[80:83], v[206:209], v[230:233], v[80:83]
	v_mfma_f32_16x16x32_bf16 v[52:55], v[198:201], v[238:241], v[52:55]
	v_mfma_f32_16x16x32_bf16 v[44:47], v[206:209], v[238:241], v[44:47]
	v_mfma_f32_16x16x32_bf16 v[100:103], v[202:205], v[218:221], v[100:103]
	v_mfma_f32_16x16x32_bf16 v[96:99], v[210:213], v[218:221], v[96:99]
	v_mfma_f32_16x16x32_bf16 v[92:95], v[202:205], v[226:229], v[92:95]
	v_mfma_f32_16x16x32_bf16 v[88:91], v[210:213], v[226:229], v[88:91]
	v_mfma_f32_16x16x32_bf16 v[84:87], v[202:205], v[234:237], v[84:87]
	v_mfma_f32_16x16x32_bf16 v[80:83], v[210:213], v[234:237], v[80:83]
	v_mfma_f32_16x16x32_bf16 v[52:55], v[202:205], v[242:245], v[52:55]
	v_mfma_f32_16x16x32_bf16 v[44:47], v[210:213], v[242:245], v[44:47]
	s_setprio 0
	s_barrier
	s_mov_b32 m0, s19
	v_lshl_add_u64 v[166:167], v[166:167], 0, s[34:35]
	s_add_u32 s14, s14, 0x40080
	ds_read_b128 v[214:217], v137 offset:49152
	ds_read_b128 v[218:221], v137 offset:50176
	ds_read_b128 v[222:225], v137 offset:51200
	ds_read_b128 v[226:229], v137 offset:52224
	ds_read_b128 v[230:233], v137 offset:53248
	ds_read_b128 v[234:237], v137 offset:54272
	ds_read_b128 v[238:241], v137 offset:55296
	ds_read_b128 v[242:245], v137 offset:56320
	global_load_lds_dwordx4 v[166:167], off
	v_lshl_add_u64 v[166:167], v[246:247], 0, s[34:35]
	s_mov_b32 m0, s30
	s_addc_u32 s15, s15, 0
	global_load_lds_dwordx4 v[166:167], off
	v_lshl_add_u64 v[166:167], s[14:15], 0, v[168:169]
	s_mov_b32 m0, s63
	s_nop 0
	global_load_lds_dwordx4 v[166:167], off
	v_lshl_add_u64 v[166:167], s[14:15], 0, v[128:129]
	s_mov_b32 m0, s24
	s_nop 0
	global_load_lds_dwordx4 v[166:167], off
	v_lshl_add_u64 v[166:167], v[248:249], 0, s[34:35]
	s_mov_b32 m0, s61
	s_nop 0
	global_load_lds_dwordx4 v[166:167], off
	v_lshl_add_u64 v[166:167], v[250:251], 0, s[34:35]
	s_mov_b32 m0, s62
	s_nop 0
	global_load_lds_dwordx4 v[166:167], off
	s_waitcnt vmcnt(8)
	s_waitcnt lgkmcnt(0)
	s_barrier
	s_setprio 1
	s_waitcnt lgkmcnt(0)
	v_mfma_f32_16x16x32_bf16 v[68:71], v[154:157], v[214:217], v[68:71]
	v_mfma_f32_16x16x32_bf16 v[64:67], v[162:165], v[214:217], v[64:67]
	v_mfma_f32_16x16x32_bf16 v[60:63], v[154:157], v[222:225], v[60:63]
	v_mfma_f32_16x16x32_bf16 v[56:59], v[162:165], v[222:225], v[56:59]
	v_mfma_f32_16x16x32_bf16 v[48:51], v[154:157], v[230:233], v[48:51]
	v_mfma_f32_16x16x32_bf16 v[40:43], v[162:165], v[230:233], v[40:43]
	v_mfma_f32_16x16x32_bf16 v[36:39], v[154:157], v[238:241], v[36:39]
	v_mfma_f32_16x16x32_bf16 v[32:35], v[162:165], v[238:241], v[32:35]
	v_mfma_f32_16x16x32_bf16 v[68:71], v[158:161], v[218:221], v[68:71]
	v_mfma_f32_16x16x32_bf16 v[64:67], v[194:197], v[218:221], v[64:67]
	v_mfma_f32_16x16x32_bf16 v[60:63], v[158:161], v[226:229], v[60:63]
	v_mfma_f32_16x16x32_bf16 v[56:59], v[194:197], v[226:229], v[56:59]
	v_mfma_f32_16x16x32_bf16 v[48:51], v[158:161], v[234:237], v[48:51]
	v_mfma_f32_16x16x32_bf16 v[40:43], v[194:197], v[234:237], v[40:43]
	v_mfma_f32_16x16x32_bf16 v[36:39], v[158:161], v[242:245], v[36:39]
	v_mfma_f32_16x16x32_bf16 v[32:35], v[194:197], v[242:245], v[32:35]
	s_setprio 0
	s_setprio 1
	v_mfma_f32_16x16x32_bf16 v[28:31], v[198:201], v[214:217], v[28:31]
	v_mfma_f32_16x16x32_bf16 v[24:27], v[206:209], v[214:217], v[24:27]
	v_mfma_f32_16x16x32_bf16 v[20:23], v[198:201], v[222:225], v[20:23]
	v_mfma_f32_16x16x32_bf16 v[16:19], v[206:209], v[222:225], v[16:19]
	v_mfma_f32_16x16x32_bf16 v[12:15], v[198:201], v[230:233], v[12:15]
	v_mfma_f32_16x16x32_bf16 v[8:11], v[206:209], v[230:233], v[8:11]
	v_mfma_f32_16x16x32_bf16 v[4:7], v[198:201], v[238:241], v[4:7]
	v_mfma_f32_16x16x32_bf16 v[0:3], v[206:209], v[238:241], v[0:3]
	v_mfma_f32_16x16x32_bf16 v[28:31], v[202:205], v[218:221], v[28:31]
	v_mfma_f32_16x16x32_bf16 v[24:27], v[210:213], v[218:221], v[24:27]
	v_mfma_f32_16x16x32_bf16 v[20:23], v[202:205], v[226:229], v[20:23]
	v_mfma_f32_16x16x32_bf16 v[16:19], v[210:213], v[226:229], v[16:19]
	v_mfma_f32_16x16x32_bf16 v[12:15], v[202:205], v[234:237], v[12:15]
	v_mfma_f32_16x16x32_bf16 v[8:11], v[210:213], v[234:237], v[8:11]
	v_mfma_f32_16x16x32_bf16 v[4:7], v[202:205], v[242:245], v[4:7]
	v_mfma_f32_16x16x32_bf16 v[0:3], v[210:213], v[242:245], v[0:3]
	s_setprio 0
	s_barrier
	s_add_i32 s60, s60, 2
	s_add_u32 s88, s88, 0x100
	s_addc_u32 s89, s89, 0
	s_cmp_lt_u32 s60, 12
	s_cbranch_scc1 .LBB0_24
	ds_read_b128 v[154:157], v138
	ds_read_b128 v[158:161], v139
	ds_read_b128 v[162:165], v140
	ds_read_b128 v[194:197], v141
	ds_read_b128 v[198:201], v142
	ds_read_b128 v[202:205], v143
	ds_read_b128 v[206:209], v144
	ds_read_b128 v[210:213], v145
	s_add_u32 s14, s96, s88
	s_addc_u32 s15, s97, s89
	s_add_u32 s14, s14, 0x4000900
	s_addc_u32 s15, s15, 0
	s_add_u32 s36, s42, s88
	s_addc_u32 s37, s43, s89
	s_cmpk_eq_i32 s88, 0x700
	s_cselect_b32 s27, s87, s15
	s_cselect_b32 s26, s86, s14
	s_cselect_b32 s15, s85, s37
	s_cselect_b32 s14, s84, s36
	v_lshl_add_u64 v[166:167], v[130:131], 0, s[88:89]
	s_add_i32 m0, s94, 0xc000
	ds_read_b128 v[214:217], v137
	ds_read_b128 v[218:221], v137 offset:1024
	ds_read_b128 v[222:225], v137 offset:2048
	ds_read_b128 v[226:229], v137 offset:3072
	ds_read_b128 v[230:233], v137 offset:4096
	ds_read_b128 v[234:237], v137 offset:5120
	ds_read_b128 v[238:241], v137 offset:6144
	ds_read_b128 v[242:245], v137 offset:7168
	global_load_lds_dwordx4 v[166:167], off
	v_lshl_add_u64 v[166:167], v[132:133], 0, s[88:89]
	s_mov_b32 m0, s48
	s_nop 0
	global_load_lds_dwordx4 v[166:167], off
	s_waitcnt vmcnt(8)
	s_waitcnt lgkmcnt(0)
	s_barrier
	s_setprio 1
	s_waitcnt lgkmcnt(0)
	v_mfma_f32_16x16x32_bf16 v[124:127], v[154:157], v[214:217], v[124:127]
	v_mfma_f32_16x16x32_bf16 v[120:123], v[162:165], v[214:217], v[120:123]
	v_mfma_f32_16x16x32_bf16 v[116:119], v[154:157], v[222:225], v[116:119]
	v_mfma_f32_16x16x32_bf16 v[112:115], v[162:165], v[222:225], v[112:115]
	v_mfma_f32_16x16x32_bf16 v[108:111], v[154:157], v[230:233], v[108:111]
	v_mfma_f32_16x16x32_bf16 v[104:107], v[162:165], v[230:233], v[104:107]
	v_mfma_f32_16x16x32_bf16 v[76:79], v[154:157], v[238:241], v[76:79]
	v_mfma_f32_16x16x32_bf16 v[72:75], v[162:165], v[238:241], v[72:75]
	v_mfma_f32_16x16x32_bf16 v[124:127], v[158:161], v[218:221], v[124:127]
	v_mfma_f32_16x16x32_bf16 v[120:123], v[194:197], v[218:221], v[120:123]
	v_mfma_f32_16x16x32_bf16 v[116:119], v[158:161], v[226:229], v[116:119]
	v_mfma_f32_16x16x32_bf16 v[112:115], v[194:197], v[226:229], v[112:115]
	v_mfma_f32_16x16x32_bf16 v[108:111], v[158:161], v[234:237], v[108:111]
	v_mfma_f32_16x16x32_bf16 v[104:107], v[194:197], v[234:237], v[104:107]
	v_mfma_f32_16x16x32_bf16 v[76:79], v[158:161], v[242:245], v[76:79]
	v_mfma_f32_16x16x32_bf16 v[72:75], v[194:197], v[242:245], v[72:75]
	s_setprio 0
	s_setprio 1
	v_mfma_f32_16x16x32_bf16 v[100:103], v[198:201], v[214:217], v[100:103]
	v_mfma_f32_16x16x32_bf16 v[96:99], v[206:209], v[214:217], v[96:99]
	v_mfma_f32_16x16x32_bf16 v[92:95], v[198:201], v[222:225], v[92:95]
	v_mfma_f32_16x16x32_bf16 v[88:91], v[206:209], v[222:225], v[88:91]
	v_mfma_f32_16x16x32_bf16 v[84:87], v[198:201], v[230:233], v[84:87]
	v_mfma_f32_16x16x32_bf16 v[80:83], v[206:209], v[230:233], v[80:83]
	v_mfma_f32_16x16x32_bf16 v[52:55], v[198:201], v[238:241], v[52:55]
	v_mfma_f32_16x16x32_bf16 v[44:47], v[206:209], v[238:241], v[44:47]
	v_mfma_f32_16x16x32_bf16 v[100:103], v[202:205], v[218:221], v[100:103]
	v_mfma_f32_16x16x32_bf16 v[96:99], v[210:213], v[218:221], v[96:99]
	v_mfma_f32_16x16x32_bf16 v[92:95], v[202:205], v[226:229], v[92:95]
	v_mfma_f32_16x16x32_bf16 v[88:91], v[210:213], v[226:229], v[88:91]
	v_mfma_f32_16x16x32_bf16 v[84:87], v[202:205], v[234:237], v[84:87]
	v_mfma_f32_16x16x32_bf16 v[80:83], v[210:213], v[234:237], v[80:83]
	v_mfma_f32_16x16x32_bf16 v[52:55], v[202:205], v[242:245], v[52:55]
	v_mfma_f32_16x16x32_bf16 v[44:47], v[210:213], v[242:245], v[44:47]
	s_setprio 0
	s_barrier
	s_mov_b32 m0, s41
	v_lshl_add_u64 v[166:167], s[14:15], 0, v[168:169]
	s_add_u32 s36, s14, 0x40000
	ds_read_b128 v[214:217], v137 offset:16384
	ds_read_b128 v[218:221], v137 offset:17408
	ds_read_b128 v[222:225], v137 offset:18432
	ds_read_b128 v[226:229], v137 offset:19456
	ds_read_b128 v[230:233], v137 offset:20480
	ds_read_b128 v[234:237], v137 offset:21504
	ds_read_b128 v[238:241], v137 offset:22528
	ds_read_b128 v[242:245], v137 offset:23552
	v_lshl_add_u64 v[246:247], s[14:15], 0, v[128:129]
	s_mov_b32 m0, s59
	s_addc_u32 s37, s15, 0
	v_lshl_add_u64 v[248:249], s[36:37], 0, v[168:169]
	s_mov_b32 m0, s95
	v_lshl_add_u64 v[250:251], s[26:27], 0, v[128:129]
	v_lshl_add_u64 v[248:249], s[36:37], 0, v[128:129]
	s_mov_b32 m0, vcc_lo
	s_nop 0
	v_lshl_add_u64 v[248:249], s[26:27], 0, v[168:169]
	s_mov_b32 m0, s94
	s_nop 0
	s_mov_b32 m0, vcc_hi
	s_nop 0
	s_waitcnt vmcnt(2)
	s_waitcnt lgkmcnt(0)
	s_barrier
	s_setprio 1
	s_waitcnt lgkmcnt(0)
	v_mfma_f32_16x16x32_bf16 v[68:71], v[154:157], v[214:217], v[68:71]
	v_mfma_f32_16x16x32_bf16 v[64:67], v[162:165], v[214:217], v[64:67]
	v_mfma_f32_16x16x32_bf16 v[60:63], v[154:157], v[222:225], v[60:63]
	v_mfma_f32_16x16x32_bf16 v[56:59], v[162:165], v[222:225], v[56:59]
	v_mfma_f32_16x16x32_bf16 v[48:51], v[154:157], v[230:233], v[48:51]
	v_mfma_f32_16x16x32_bf16 v[40:43], v[162:165], v[230:233], v[40:43]
	v_mfma_f32_16x16x32_bf16 v[36:39], v[154:157], v[238:241], v[36:39]
	v_mfma_f32_16x16x32_bf16 v[32:35], v[162:165], v[238:241], v[32:35]
	v_mfma_f32_16x16x32_bf16 v[68:71], v[158:161], v[218:221], v[68:71]
	v_mfma_f32_16x16x32_bf16 v[64:67], v[194:197], v[218:221], v[64:67]
	v_mfma_f32_16x16x32_bf16 v[60:63], v[158:161], v[226:229], v[60:63]
	v_mfma_f32_16x16x32_bf16 v[56:59], v[194:197], v[226:229], v[56:59]
	v_mfma_f32_16x16x32_bf16 v[48:51], v[158:161], v[234:237], v[48:51]
	v_mfma_f32_16x16x32_bf16 v[40:43], v[194:197], v[234:237], v[40:43]
	v_mfma_f32_16x16x32_bf16 v[36:39], v[158:161], v[242:245], v[36:39]
	v_mfma_f32_16x16x32_bf16 v[32:35], v[194:197], v[242:245], v[32:35]
	s_setprio 0
	s_setprio 1
	v_mfma_f32_16x16x32_bf16 v[28:31], v[198:201], v[214:217], v[28:31]
	v_mfma_f32_16x16x32_bf16 v[24:27], v[206:209], v[214:217], v[24:27]
	v_mfma_f32_16x16x32_bf16 v[20:23], v[198:201], v[222:225], v[20:23]
	v_mfma_f32_16x16x32_bf16 v[16:19], v[206:209], v[222:225], v[16:19]
	v_mfma_f32_16x16x32_bf16 v[12:15], v[198:201], v[230:233], v[12:15]
	v_mfma_f32_16x16x32_bf16 v[8:11], v[206:209], v[230:233], v[8:11]
	v_mfma_f32_16x16x32_bf16 v[4:7], v[198:201], v[238:241], v[4:7]
	v_mfma_f32_16x16x32_bf16 v[0:3], v[206:209], v[238:241], v[0:3]
	v_mfma_f32_16x16x32_bf16 v[28:31], v[202:205], v[218:221], v[28:31]
	v_mfma_f32_16x16x32_bf16 v[24:27], v[210:213], v[218:221], v[24:27]
	v_mfma_f32_16x16x32_bf16 v[20:23], v[202:205], v[226:229], v[20:23]
	v_mfma_f32_16x16x32_bf16 v[16:19], v[210:213], v[226:229], v[16:19]
	v_mfma_f32_16x16x32_bf16 v[12:15], v[202:205], v[234:237], v[12:15]
	v_mfma_f32_16x16x32_bf16 v[8:11], v[210:213], v[234:237], v[8:11]
	v_mfma_f32_16x16x32_bf16 v[4:7], v[202:205], v[242:245], v[4:7]
	v_mfma_f32_16x16x32_bf16 v[0:3], v[210:213], v[242:245], v[0:3]
	s_setprio 0
	s_barrier
	ds_read_b128 v[154:157], v146
	ds_read_b128 v[158:161], v147
	ds_read_b128 v[162:165], v148
	ds_read_b128 v[194:197], v149
	ds_read_b128 v[198:201], v150
	ds_read_b128 v[202:205], v151
	ds_read_b128 v[206:209], v152
	ds_read_b128 v[210:213], v153
	s_add_u32 s26, s26, 0x40000
	s_addc_u32 s27, s27, 0
	s_mov_b32 m0, s28
	v_lshl_add_u64 v[180:181], s[26:27], 0, v[168:169]
	ds_read_b128 v[214:217], v137 offset:32768
	ds_read_b128 v[218:221], v137 offset:33792
	ds_read_b128 v[222:225], v137 offset:34816
	ds_read_b128 v[226:229], v137 offset:35840
	ds_read_b128 v[230:233], v137 offset:36864
	ds_read_b128 v[234:237], v137 offset:37888
	ds_read_b128 v[238:241], v137 offset:38912
	ds_read_b128 v[242:245], v137 offset:39936
	v_lshl_add_u64 v[180:181], s[26:27], 0, v[128:129]
	s_mov_b32 m0, s29
	s_nop 0
	s_waitcnt vmcnt(0)
	s_waitcnt lgkmcnt(0)
	s_barrier
	s_setprio 1
	s_waitcnt lgkmcnt(0)
	v_mfma_f32_16x16x32_bf16 v[124:127], v[154:157], v[214:217], v[124:127]
	v_mfma_f32_16x16x32_bf16 v[120:123], v[162:165], v[214:217], v[120:123]
	v_mfma_f32_16x16x32_bf16 v[116:119], v[154:157], v[222:225], v[116:119]
	v_mfma_f32_16x16x32_bf16 v[112:115], v[162:165], v[222:225], v[112:115]
	v_mfma_f32_16x16x32_bf16 v[108:111], v[154:157], v[230:233], v[108:111]
	v_mfma_f32_16x16x32_bf16 v[104:107], v[162:165], v[230:233], v[104:107]
	v_mfma_f32_16x16x32_bf16 v[76:79], v[154:157], v[238:241], v[76:79]
	v_mfma_f32_16x16x32_bf16 v[72:75], v[162:165], v[238:241], v[72:75]
	v_mfma_f32_16x16x32_bf16 v[124:127], v[158:161], v[218:221], v[124:127]
	v_mfma_f32_16x16x32_bf16 v[120:123], v[194:197], v[218:221], v[120:123]
	v_mfma_f32_16x16x32_bf16 v[116:119], v[158:161], v[226:229], v[116:119]
	v_mfma_f32_16x16x32_bf16 v[112:115], v[194:197], v[226:229], v[112:115]
	v_mfma_f32_16x16x32_bf16 v[108:111], v[158:161], v[234:237], v[108:111]
	v_mfma_f32_16x16x32_bf16 v[104:107], v[194:197], v[234:237], v[104:107]
	v_mfma_f32_16x16x32_bf16 v[76:79], v[158:161], v[242:245], v[76:79]
	v_mfma_f32_16x16x32_bf16 v[72:75], v[194:197], v[242:245], v[72:75]
	s_setprio 0
	s_setprio 1
	v_mfma_f32_16x16x32_bf16 v[100:103], v[198:201], v[214:217], v[100:103]
	v_mfma_f32_16x16x32_bf16 v[96:99], v[206:209], v[214:217], v[96:99]
	v_mfma_f32_16x16x32_bf16 v[92:95], v[198:201], v[222:225], v[92:95]
	v_mfma_f32_16x16x32_bf16 v[88:91], v[206:209], v[222:225], v[88:91]
	v_mfma_f32_16x16x32_bf16 v[84:87], v[198:201], v[230:233], v[84:87]
	v_mfma_f32_16x16x32_bf16 v[80:83], v[206:209], v[230:233], v[80:83]
	v_mfma_f32_16x16x32_bf16 v[52:55], v[198:201], v[238:241], v[52:55]
	v_mfma_f32_16x16x32_bf16 v[44:47], v[206:209], v[238:241], v[44:47]
	v_mfma_f32_16x16x32_bf16 v[100:103], v[202:205], v[218:221], v[100:103]
	v_mfma_f32_16x16x32_bf16 v[96:99], v[210:213], v[218:221], v[96:99]
	v_mfma_f32_16x16x32_bf16 v[92:95], v[202:205], v[226:229], v[92:95]
	v_mfma_f32_16x16x32_bf16 v[88:91], v[210:213], v[226:229], v[88:91]
	v_mfma_f32_16x16x32_bf16 v[84:87], v[202:205], v[234:237], v[84:87]
	v_mfma_f32_16x16x32_bf16 v[80:83], v[210:213], v[234:237], v[80:83]
	v_mfma_f32_16x16x32_bf16 v[52:55], v[202:205], v[242:245], v[52:55]
	v_mfma_f32_16x16x32_bf16 v[44:47], v[210:213], v[242:245], v[44:47]
	s_setprio 0
	s_barrier
	s_mov_b32 m0, s19
	v_lshl_add_u64 v[166:167], v[166:167], 0, s[34:35]
	s_add_u32 s14, s14, 0x40080
	ds_read_b128 v[214:217], v137 offset:49152
	ds_read_b128 v[218:221], v137 offset:50176
	ds_read_b128 v[222:225], v137 offset:51200
	ds_read_b128 v[226:229], v137 offset:52224
	ds_read_b128 v[230:233], v137 offset:53248
	ds_read_b128 v[234:237], v137 offset:54272
	ds_read_b128 v[238:241], v137 offset:55296
	ds_read_b128 v[242:245], v137 offset:56320
	v_lshl_add_u64 v[166:167], v[246:247], 0, s[34:35]
	s_mov_b32 m0, s30
	s_addc_u32 s15, s15, 0
	v_lshl_add_u64 v[166:167], s[14:15], 0, v[168:169]
	s_mov_b32 m0, s63
	s_nop 0
	v_lshl_add_u64 v[166:167], s[14:15], 0, v[128:129]
	s_mov_b32 m0, s24
	s_nop 0
	v_lshl_add_u64 v[166:167], v[248:249], 0, s[34:35]
	s_mov_b32 m0, s61
	s_nop 0
	v_lshl_add_u64 v[166:167], v[250:251], 0, s[34:35]
	s_mov_b32 m0, s62
	s_nop 0
	s_waitcnt vmcnt(0)
	s_waitcnt lgkmcnt(0)
	s_barrier
	s_setprio 1
	s_waitcnt lgkmcnt(0)
	v_mfma_f32_16x16x32_bf16 v[68:71], v[154:157], v[214:217], v[68:71]
	v_mfma_f32_16x16x32_bf16 v[64:67], v[162:165], v[214:217], v[64:67]
	v_mfma_f32_16x16x32_bf16 v[60:63], v[154:157], v[222:225], v[60:63]
	v_mfma_f32_16x16x32_bf16 v[56:59], v[162:165], v[222:225], v[56:59]
	v_mfma_f32_16x16x32_bf16 v[48:51], v[154:157], v[230:233], v[48:51]
	v_mfma_f32_16x16x32_bf16 v[40:43], v[162:165], v[230:233], v[40:43]
	v_mfma_f32_16x16x32_bf16 v[36:39], v[154:157], v[238:241], v[36:39]
	v_mfma_f32_16x16x32_bf16 v[32:35], v[162:165], v[238:241], v[32:35]
	v_mfma_f32_16x16x32_bf16 v[68:71], v[158:161], v[218:221], v[68:71]
	v_mfma_f32_16x16x32_bf16 v[64:67], v[194:197], v[218:221], v[64:67]
	v_mfma_f32_16x16x32_bf16 v[60:63], v[158:161], v[226:229], v[60:63]
	v_mfma_f32_16x16x32_bf16 v[56:59], v[194:197], v[226:229], v[56:59]
	v_mfma_f32_16x16x32_bf16 v[48:51], v[158:161], v[234:237], v[48:51]
	v_mfma_f32_16x16x32_bf16 v[40:43], v[194:197], v[234:237], v[40:43]
	v_mfma_f32_16x16x32_bf16 v[36:39], v[158:161], v[242:245], v[36:39]
	v_mfma_f32_16x16x32_bf16 v[32:35], v[194:197], v[242:245], v[32:35]
	s_setprio 0
	s_setprio 1
	v_mfma_f32_16x16x32_bf16 v[28:31], v[198:201], v[214:217], v[28:31]
	v_mfma_f32_16x16x32_bf16 v[24:27], v[206:209], v[214:217], v[24:27]
	v_mfma_f32_16x16x32_bf16 v[20:23], v[198:201], v[222:225], v[20:23]
	v_mfma_f32_16x16x32_bf16 v[16:19], v[206:209], v[222:225], v[16:19]
	v_mfma_f32_16x16x32_bf16 v[12:15], v[198:201], v[230:233], v[12:15]
	v_mfma_f32_16x16x32_bf16 v[8:11], v[206:209], v[230:233], v[8:11]
	v_mfma_f32_16x16x32_bf16 v[4:7], v[198:201], v[238:241], v[4:7]
	v_mfma_f32_16x16x32_bf16 v[0:3], v[206:209], v[238:241], v[0:3]
	v_mfma_f32_16x16x32_bf16 v[28:31], v[202:205], v[218:221], v[28:31]
	v_mfma_f32_16x16x32_bf16 v[24:27], v[210:213], v[218:221], v[24:27]
	v_mfma_f32_16x16x32_bf16 v[20:23], v[202:205], v[226:229], v[20:23]
	v_mfma_f32_16x16x32_bf16 v[16:19], v[210:213], v[226:229], v[16:19]
	v_mfma_f32_16x16x32_bf16 v[12:15], v[202:205], v[234:237], v[12:15]
	v_mfma_f32_16x16x32_bf16 v[8:11], v[210:213], v[234:237], v[8:11]
	v_mfma_f32_16x16x32_bf16 v[4:7], v[202:205], v[242:245], v[4:7]
	v_mfma_f32_16x16x32_bf16 v[0:3], v[210:213], v[242:245], v[0:3]
	s_setprio 0
	s_barrier
	s_add_i32 s60, s60, 2
	s_add_u32 s88, s88, 0x100
	s_addc_u32 s89, s89, 0
	s_cmp_lt_u32 s60, 14
	v_lshrrev_b32_e32 v248, 1, v192
	v_and_b32_e32 v249, 1, v192
	v_lshlrev_b32_e32 v248, 11, v248
	v_lshl_or_b32 v248, v249, 7, v248
	v_add_u32_e32 v248, 0x3f8000, v248
	v_mov_b32_e32 v249, 0
	v_lshl_add_u64 v[248:249], s[86:87], 0, v[248:249]
	v_mov_b32_e32 v247, 0
	v_sub_u32_e32 v246, v248, v248
	v_lshrrev_b32_e32 v246, 1, v192
	v_and_b32_e32 v243, 1, v192
	v_lshlrev_b32_e32 v246, 11, v246
	v_lshl_or_b32 v246, v243, 7, v246
	v_lshl_add_u64 v[246:247], s[84:85], 0, v[246:247]
	s_waitcnt vmcnt(0)
	s_cmpk_gt_u32 s92, 0xff
	s_cbranch_scc1 .LBB0_27
	s_barrier

.LBB0_29:
	s_or_b64 exec, exec, s[14:15]
	v_mov_b32_e32 v114, v192
	s_waitcnt lgkmcnt(0)
	s_barrier
	s_lshl_b32 s26, s40, 7
	v_lshlrev_b32_e32 v80, 3, v114
	v_and_b32_e32 v115, 0x78, v80
	v_or_b32_e32 v112, s26, v115
	v_ashrrev_i32_e32 v113, 31, v112
	s_mov_b64 s[52:53], s[44:45]
	v_readlane_b32 s44, v255, 16
	v_lshlrev_b64 v[92:93], 2, v[112:113]
	v_readlane_b32 s45, v255, 17
	v_lshl_add_u64 v[84:85], s[56:57], 0, v[92:93]
	v_lshl_add_u64 v[88:89], s[52:53], 0, v[92:93]
	v_lshl_add_u64 v[94:95], s[44:45], 0, v[92:93]
	v_lshl_add_u64 v[108:109], s[48:49], 0, v[92:93]
	global_load_dwordx4 v[80:83], v[84:85], off offset:16
	global_load_dwordx4 v[96:99], v[84:85], off
	s_nop 0
	global_load_dwordx4 v[84:87], v[88:89], off offset:16
	global_load_dwordx4 v[100:103], v[88:89], off
	s_nop 0
	global_load_dwordx4 v[88:91], v[94:95], off offset:16
	global_load_dwordx4 v[104:107], v[94:95], off
	s_nop 0
	global_load_dwordx4 v[92:95], v[108:109], off offset:16
	s_nop 0
	global_load_dwordx4 v[108:111], v[108:109], off
	v_ashrrev_i32_e32 v116, 4, v114
	v_lshrrev_b32_e32 v114, 4, v114
	v_bfi_b32 v118, -4, v116, v114
	s_movk_i32 s5, 0x7f
	v_add_u32_e32 v114, s91, v118
	v_cmp_gt_i32_e32 vcc, s5, v118
	s_mov_b32 s5, 0x14000
	v_cmp_gt_i32_e64 s[40:41], s5, v114
	s_movk_i32 s5, 0x410
	v_lshlrev_b32_e32 v116, 2, v115
	v_mul_lo_u32 v117, v118, s5
	s_and_b64 s[28:29], vcc, s[40:41]
	v_add_u32_e32 v120, v116, v117
	v_lshl_add_u32 v119, v115, 2, v117
	s_and_saveexec_b64 s[14:15], s[28:29]
	s_mov_b32 s92, 0
	s_mov_b32 s93, 0x403e0000
	s_cbranch_execz .LBB0_31
	v_cmp_gt_i32_e32 vcc, s33, v114
	ds_read_b128 v[122:125], v120
	ds_read_b128 v[130:133], v120 offset:16
	ds_read_b128 v[136:139], v119 offset:1040
	ds_read_b128 v[140:143], v119 offset:1056
	ds_read_b128 v[144:147], v119 offset:2080
	ds_read_b128 v[148:151], v119 offset:2096
	ds_read_b128 v[152:155], v119 offset:1552
	ds_read_b128 v[156:159], v119 offset:1568
	v_cndmask_b32_e32 v115, v178, v179, vcc
	v_and_b32_e32 v115, v115, v114
	v_cndmask_b32_e32 v121, v175, v176, vcc
	v_cmp_ne_u32_e32 vcc, 0, v115
	v_add_u32_e32 v115, 1, v115
	s_mov_b32 s24, 0xc0135761
	s_waitcnt lgkmcnt(6)
	v_cndmask_b32_e32 v127, 0, v133, vcc
	v_cndmask_b32_e32 v126, 0, v132, vcc
	v_cndmask_b32_e32 v131, 0, v131, vcc
	v_cndmask_b32_e32 v130, 0, v130, vcc
	v_cndmask_b32_e32 v125, 0, v125, vcc
	v_cndmask_b32_e32 v124, 0, v124, vcc
	v_cndmask_b32_e32 v123, 0, v123, vcc
	v_cndmask_b32_e32 v122, 0, v122, vcc
	v_cmp_lt_u32_e32 vcc, v115, v121
	v_ashrrev_i32_e32 v115, 31, v114
	v_lshlrev_b64 v[114:115], 13, v[114:115]
	s_waitcnt lgkmcnt(3)
	v_cndmask_b32_e32 v145, 0, v145, vcc
	v_cndmask_b32_e32 v144, 0, v144, vcc
	s_waitcnt vmcnt(0)
	global_load_dword v250, v[248:249], off
	global_load_dword v251, v[246:247], off
	global_load_dword v244, v[248:249], off offset:256
	global_load_dword v245, v[246:247], off offset:256
	v_pk_fma_f32 v[144:145], v[104:105], v[144:145], v[108:109]
	v_cndmask_b32_e32 v147, 0, v147, vcc
	v_pk_fma_f32 v[136:137], v[100:101], v[136:137], v[144:145]
	v_mov_b64_e32 v[144:145], s[24:25]
	v_pk_fma_f32 v[122:123], v[96:97], v[122:123], v[136:137]
	s_mov_b32 s24, 0x3dd2d3e8
	v_pk_mul_f32 v[136:137], v[122:123], v[122:123]
	v_cndmask_b32_e32 v146, 0, v146, vcc
	v_pk_fma_f32 v[136:137], v[136:137], s[24:25], v[144:145] op_sel_hi:[1,0,0] neg_lo:[1,0,0] neg_hi:[1,0,0]
	s_waitcnt lgkmcnt(2)
	v_cndmask_b32_e32 v133, 0, v151, vcc
	v_pk_mul_f32 v[136:137], v[122:123], v[136:137]
	v_cndmask_b32_e32 v132, 0, v150, vcc
	v_exp_f32_e32 v136, v136
	v_exp_f32_e32 v137, v137
	v_cndmask_b32_e32 v149, 0, v149, vcc
	v_cndmask_b32_e32 v148, 0, v148, vcc
	v_pk_fma_f32 v[132:133], v[90:91], v[132:133], v[94:95]
	v_pk_add_f32 v[136:137], v[136:137], 1.0 op_sel_hi:[1,0]
	v_pk_fma_f32 v[132:133], v[86:87], v[142:143], v[132:133]
	v_rcp_f32_e32 v136, v136
	v_rcp_f32_e32 v137, v137
	v_pk_fma_f32 v[126:127], v[82:83], v[126:127], v[132:133]
	v_lshl_add_u64 v[114:115], s[46:47], 0, v[114:115]
	v_pk_mul_f32 v[132:133], v[126:127], v[126:127]
	v_pk_mul_f32 v[122:123], v[122:123], v[136:137]
	v_pk_fma_f32 v[136:137], v[106:107], v[146:147], v[110:111]
	v_pk_fma_f32 v[132:133], v[132:133], s[24:25], v[144:145] op_sel_hi:[1,0,0] neg_lo:[1,0,0] neg_hi:[1,0,0]
	v_pk_fma_f32 v[136:137], v[102:103], v[138:139], v[136:137]
	v_pk_mul_f32 v[132:133], v[126:127], v[132:133]
	v_pk_fma_f32 v[124:125], v[98:99], v[124:125], v[136:137]
	v_exp_f32_e32 v132, v132
	v_pk_mul_f32 v[136:137], v[124:125], v[124:125]
	v_exp_f32_e32 v133, v133
	v_pk_fma_f32 v[136:137], v[136:137], s[24:25], v[144:145] op_sel_hi:[1,0,0] neg_lo:[1,0,0] neg_hi:[1,0,0]
	s_waitcnt lgkmcnt(1)
	v_pk_mul_f32 v[122:123], v[152:153], v[122:123]
	v_pk_mul_f32 v[136:137], v[124:125], v[136:137]
	v_pk_add_f32 v[132:133], v[132:133], 1.0 op_sel_hi:[1,0]
	v_exp_f32_e32 v136, v136
	v_exp_f32_e32 v137, v137
	v_rcp_f32_e32 v132, v132
	v_rcp_f32_e32 v133, v133
	v_cvt_pk_bf16_f32 v122, v122, v123
	v_pk_add_f32 v[136:137], v[136:137], 1.0 op_sel_hi:[1,0]
	v_lshl_add_u64 v[114:115], v[112:113], 1, v[114:115]
	v_rcp_f32_e32 v136, v136
	v_rcp_f32_e32 v137, v137
	v_pk_mul_f32 v[126:127], v[126:127], v[132:133]
	v_pk_mul_f32 v[124:125], v[124:125], v[136:137]
	v_pk_fma_f32 v[136:137], v[88:89], v[148:149], v[92:93]
	v_pk_mul_f32 v[124:125], v[154:155], v[124:125]
	v_pk_fma_f32 v[136:137], v[84:85], v[140:141], v[136:137]
	s_waitcnt lgkmcnt(0)
	v_pk_mul_f32 v[126:127], v[158:159], v[126:127]
	v_pk_fma_f32 v[130:131], v[80:81], v[130:131], v[136:137]
	v_cvt_pk_bf16_f32 v123, v124, v125
	v_pk_mul_f32 v[136:137], v[130:131], v[130:131]
	v_cvt_pk_bf16_f32 v125, v126, v127
	v_pk_fma_f32 v[136:137], v[136:137], s[24:25], v[144:145] op_sel_hi:[1,0,0] neg_lo:[1,0,0] neg_hi:[1,0,0]
	s_nop 0
	v_pk_mul_f32 v[136:137], v[130:131], v[136:137]
	s_nop 0
	v_exp_f32_e32 v136, v136
	v_exp_f32_e32 v137, v137
	s_nop 0
	v_pk_add_f32 v[136:137], v[136:137], 1.0 op_sel_hi:[1,0]
	s_nop 0
	v_rcp_f32_e32 v136, v136
	v_rcp_f32_e32 v137, v137
	s_nop 0
	v_pk_mul_f32 v[130:131], v[130:131], v[136:137]
	s_nop 0
	v_pk_mul_f32 v[130:131], v[156:157], v[130:131]
	s_nop 0
	v_cvt_pk_bf16_f32 v124, v130, v131
	global_store_dwordx4 v[114:115], v[122:125], off

.Lp4_skip_b0:
	s_waitcnt vmcnt(0)
	s_branch .LBB0_41
	s_nop 0
	s_nop 0
	s_nop 0
	s_nop 0
	s_nop 0
	s_nop 0
	s_nop 0
	s_nop 0
	s_nop 0
